# P9 rewritten by hand: one sample row per workgroup (128 WGs x 8 waves x 256 cols) instead of one row per wave on 16 WGs
# speedup vs baseline: 1.0069x; 1.0069x over previous
; __global__ void __launch_bounds__(NTHR) hymba_fwd(Params P) {
;     ...
;     if (IN(9)) {
;         PHASE_IDS
;         for (int row = (G == 256 ? MPR : 0) + gwave; row < MV; row += gwaves) {
;             float* p = out + (size_t)row * D; f32x4 v[8]; float s = 0.f;
; #pragma unroll
;             for (int i = 0; i < 8; ++i) v[i] = *(const f32x4*)(p + (i * 64 + lane) * 4);
;             if (row >= MPR) {
; #pragma unroll
;                 for (int i = 0; i < 8; ++i)
; #pragma unroll
;                     for (int ks = 0; ks < KS8; ++ks) v[i] = v[i] + *(const f32x4*)(Part8 + ((size_t)ks * MSA + (row - MPR)) * D + (i * 64 + lane) * 4);
;             }
; #pragma unroll
;             for (int i = 0; i < 8; ++i) s += (v[i][0] * v[i][0] + v[i][1] * v[i][1]) + (v[i][2] * v[i][2] + v[i][3] * v[i][3]);
;             s = wsum(s); const float rstd = rsqrtf(s * (1.0f / D) + RMS_EPS);
; #pragma unroll
;             for (int i = 0; i < 8; ++i) { const int c = (i * 64 + lane) * 4; *(f32x4*)(p + c) = v[i] * rstd * *(const f32x4*)(norm_final + c); }
;         }
.LBB0_1418:
	s_cmp_eq_u32 s95, 9
	s_cselect_b64 s[0:1], -1, 0
	s_or_b64 s[0:1], s[92:93], s[0:1]
	s_andn2_b64 vcc, exec, s[0:1]
	s_cbranch_vccnz .LBB0_1424
	s_cmpk_lg_i32 s3, 0x100
	s_cbranch_scc1 .Lp9_generic
	s_cmpk_gt_u32 s2, 0x7f
	s_cbranch_scc1 .LBB0_1424
	v_readfirstlane_b32 s0, v196
	v_and_b32_e32 v0, 63, v196
	v_readlane_b32 s4, v234, 0
	v_readlane_b32 s5, v234, 1
	s_lshr_b32 s0, s0, 6
	v_lshlrev_b32_e32 v0, 4, v0
	s_lshl_b32 s1, s0, 10
	v_add_u32_e32 v0, s1, v0
	s_sub_u32 s4, s4, 0xe8
	s_subb_u32 s5, s5, 0
	s_load_dwordx2 s[6:7], s[4:5], 0xc8
	s_addk_i32 s2, 0x2000
	s_lshl_b32 s9, s2, 13
	s_add_u32 s10, s88, s9
	s_addc_u32 s11, s89, 0
	s_add_i32 s9, s9, 0xfc000000
	s_add_u32 s12, s90, 0x5e00000
	s_addc_u32 s13, s91, 0
	s_add_u32 s12, s12, s9
	s_addc_u32 s13, s13, 0
	global_load_dwordx4 v[4:7], v0, s[10:11]
	global_load_dwordx4 v[8:11], v0, s[12:13]
	s_add_u32 s12, s12, 0x100000
	s_addc_u32 s13, s13, 0
	global_load_dwordx4 v[12:15], v0, s[12:13]
	s_add_u32 s12, s12, 0x100000
	s_addc_u32 s13, s13, 0
	global_load_dwordx4 v[16:19], v0, s[12:13]
	s_add_u32 s12, s12, 0x100000
	s_addc_u32 s13, s13, 0
	global_load_dwordx4 v[20:23], v0, s[12:13]
	s_add_u32 s12, s12, 0x100000
	s_addc_u32 s13, s13, 0
	global_load_dwordx4 v[24:27], v0, s[12:13]
	s_add_u32 s12, s12, 0x100000
	s_addc_u32 s13, s13, 0
	global_load_dwordx4 v[28:31], v0, s[12:13]
	s_add_u32 s12, s12, 0x100000
	s_addc_u32 s13, s13, 0
	global_load_dwordx4 v[32:35], v0, s[12:13]
	s_add_u32 s12, s12, 0x100000
	s_addc_u32 s13, s13, 0
	global_load_dwordx4 v[36:39], v0, s[12:13]
	s_add_u32 s12, s12, 0x100000
	s_addc_u32 s13, s13, 0
	global_load_dwordx4 v[40:43], v0, s[12:13]
	s_add_u32 s12, s12, 0x100000
	s_addc_u32 s13, s13, 0
	global_load_dwordx4 v[44:47], v0, s[12:13]
	s_add_u32 s12, s12, 0x100000
	s_addc_u32 s13, s13, 0
	global_load_dwordx4 v[48:51], v0, s[12:13]
	s_waitcnt lgkmcnt(0)
	global_load_dwordx4 v[52:55], v0, s[6:7]
	s_waitcnt vmcnt(11)
	v_pk_add_f32 v[4:5], v[4:5], v[8:9]
	v_pk_add_f32 v[6:7], v[6:7], v[10:11]
	s_waitcnt vmcnt(10)
	v_pk_add_f32 v[4:5], v[4:5], v[12:13]
	v_pk_add_f32 v[6:7], v[6:7], v[14:15]
	s_waitcnt vmcnt(9)
	v_pk_add_f32 v[4:5], v[4:5], v[16:17]
	v_pk_add_f32 v[6:7], v[6:7], v[18:19]
	s_waitcnt vmcnt(8)
	v_pk_add_f32 v[4:5], v[4:5], v[20:21]
	v_pk_add_f32 v[6:7], v[6:7], v[22:23]
	s_waitcnt vmcnt(7)
	v_pk_add_f32 v[4:5], v[4:5], v[24:25]
	v_pk_add_f32 v[6:7], v[6:7], v[26:27]
	s_waitcnt vmcnt(6)
	v_pk_add_f32 v[4:5], v[4:5], v[28:29]
	v_pk_add_f32 v[6:7], v[6:7], v[30:31]
	s_waitcnt vmcnt(5)
	v_pk_add_f32 v[4:5], v[4:5], v[32:33]
	v_pk_add_f32 v[6:7], v[6:7], v[34:35]
	s_waitcnt vmcnt(4)
	v_pk_add_f32 v[4:5], v[4:5], v[36:37]
	v_pk_add_f32 v[6:7], v[6:7], v[38:39]
	s_waitcnt vmcnt(3)
	v_pk_add_f32 v[4:5], v[4:5], v[40:41]
	v_pk_add_f32 v[6:7], v[6:7], v[42:43]
	s_waitcnt vmcnt(2)
	v_pk_add_f32 v[4:5], v[4:5], v[44:45]
	v_pk_add_f32 v[6:7], v[6:7], v[46:47]
	s_waitcnt vmcnt(1)
	v_pk_add_f32 v[4:5], v[4:5], v[48:49]
	v_pk_add_f32 v[6:7], v[6:7], v[50:51]
	v_pk_mul_f32 v[56:57], v[4:5], v[4:5]
	v_pk_fma_f32 v[56:57], v[6:7], v[6:7], v[56:57]
	s_lshl_b32 s18, s0, 2
	v_mov_b32_e32 v58, s18
	v_add_f32_e32 v56, v56, v57
	s_nop 1
	v_add_f32_dpp v56, v56, v56 quad_perm:[1,0,3,2] row_mask:0xf bank_mask:0xf bound_ctrl:1
	s_nop 1
	v_add_f32_dpp v56, v56, v56 quad_perm:[2,3,0,1] row_mask:0xf bank_mask:0xf bound_ctrl:1
	s_nop 1
	v_add_f32_dpp v56, v56, v56 row_half_mirror row_mask:0xf bank_mask:0xf bound_ctrl:1
	s_nop 1
	v_add_f32_dpp v56, v56, v56 row_mirror row_mask:0xf bank_mask:0xf bound_ctrl:1
	s_nop 1
	v_readlane_b32 s14, v56, 0
	v_readlane_b32 s15, v56, 16
	v_readlane_b32 s16, v56, 32
	v_readlane_b32 s17, v56, 48
	s_nop 1
	v_mov_b32_e32 v57, s14
	v_add_f32_e32 v57, s15, v57
	v_add_f32_e32 v57, s16, v57
	v_add_f32_e32 v57, s17, v57
	ds_write_b32 v58, v57
	v_mov_b32_e32 v58, 0
	s_waitcnt lgkmcnt(0)
	s_barrier
	ds_read_b128 v[60:63], v58
	ds_read_b128 v[64:67], v58 offset:16
	v_mov_b32_e32 v68, 0x3a000000
	v_mov_b32_e32 v69, 0x358637bd
	s_waitcnt lgkmcnt(0)
	v_add_f32_e32 v60, v60, v61
	v_add_f32_e32 v62, v62, v63
	v_add_f32_e32 v64, v64, v65
	v_add_f32_e32 v66, v66, v67
	v_add_f32_e32 v60, v60, v62
	v_add_f32_e32 v64, v64, v66
	v_add_f32_e32 v60, v60, v64
	v_fma_f32 v60, v60, v68, v69
	v_rsq_f32_e32 v60, v60
	s_waitcnt vmcnt(0)
	s_nop 0
	v_pk_mul_f32 v[4:5], v[4:5], v[60:61] op_sel_hi:[1,0]
	v_pk_mul_f32 v[6:7], v[6:7], v[60:61] op_sel_hi:[1,0]
	v_pk_mul_f32 v[4:5], v[4:5], v[52:53]
	v_pk_mul_f32 v[6:7], v[6:7], v[54:55]
	global_store_dwordx4 v0, v[4:7], s[10:11]
	s_branch .LBB0_1424
.Lp9_generic:
	s_lshl_b32 s0, s2, 3
	s_cmpk_eq_i32 s3, 0x100
	s_cselect_b32 s1, 0x2000, 0
	s_add_i32 s1, s1, s0
	v_ashrrev_i32_e32 v0, 6, v196
	v_add_u32_e32 v112, s1, v0
	s_movk_i32 s0, 0x2080
	v_cmp_gt_i32_e32 vcc, s0, v112
	s_and_saveexec_b64 s[0:1], vcc
	s_cbranch_execz .LBB0_1424
	v_lshlrev_b32_e32 v0, 2, v196
	s_waitcnt lgkmcnt(0)
	v_and_b32_e32 v1, 0xfc, v0
	v_mov_b32_e32 v115, 0
	v_lshlrev_b32_e32 v114, 2, v1
	s_waitcnt vmcnt(0)
	v_or_b32_e32 v6, 0x1000, v114
	v_mov_b32_e32 v7, v115
	v_ashrrev_i32_e32 v113, 31, v112
	v_or_b32_e32 v0, 0x100, v1
	v_or_b32_e32 v2, 0x200, v1
	v_or_b32_e32 v4, 0x300, v1
	v_lshl_add_u64 v[118:119], s[46:47], 0, v[6:7]
	v_lshl_add_u64 v[128:129], s[86:87], 0, v[6:7]
	v_lshlrev_b64 v[6:7], 13, v[112:113]
	v_and_b32_e32 v1, 63, v196
	v_lshl_or_b32 v6, v1, 4, v6
	v_or_b32_e32 v8, 0x1400, v114
	v_mov_b32_e32 v9, v115
	v_or_b32_e32 v10, 0x1800, v114
	v_mov_b32_e32 v11, v115
	v_or_b32_e32 v12, 0x1c00, v114
	v_mov_b32_e32 v13, v115
	v_lshl_add_u64 v[6:7], s[88:89], 0, v[6:7]
	s_mov_b64 s[0:1], 0x1c00
	s_ashr_i32 s29, s28, 31
	s_movk_i32 s4, 0xe400
	s_movk_i32 s6, 0xe800
	s_movk_i32 s8, 0xec00
	v_lshl_add_u64 v[116:117], s[46:47], 0, v[114:115]
	v_lshl_add_u64 v[120:121], s[46:47], 0, v[8:9]
	v_lshl_add_u64 v[122:123], s[46:47], 0, v[10:11]
	v_lshl_add_u64 v[124:125], s[46:47], 0, v[12:13]
	v_lshl_add_u64 v[126:127], s[86:87], 0, v[114:115]
	v_lshl_add_u64 v[130:131], s[86:87], 0, v[8:9]
	v_lshl_add_u64 v[132:133], s[86:87], 0, v[10:11]
	v_lshl_add_u64 v[134:135], s[86:87], 0, v[12:13]
	v_lshl_add_u64 v[136:137], v[6:7], 0, s[0:1]
	s_lshl_b64 s[0:1], s[28:29], 13
	s_mov_b64 s[2:3], 0
	s_mov_b32 s5, -1
	s_mov_b32 s7, -1
	s_mov_b32 s9, -1
	s_movk_i32 s12, 0x1fff
	s_mov_b32 s13, 0x100000
	s_mov_b32 s14, 0x200000
	s_mov_b32 s15, 0x300000
	s_mov_b32 s16, 0x400000
	s_mov_b32 s17, 0x500000
	s_mov_b32 s18, 0x600000
	s_mov_b32 s19, 0x700000
	s_mov_b32 s20, 0x800000
	s_mov_b32 s21, 0x900000
	s_mov_b32 s22, 0xa00000
	v_lshlrev_b32_e32 v138, 2, v0
	v_lshlrev_b32_e32 v140, 2, v2
	v_lshlrev_b32_e32 v142, 2, v4
	v_mov_b32_e32 v113, 0x358637bd
	s_movk_i32 s23, 0x207f
	v_mov_b32_e32 v146, 0x3a000000
	s_branch .LBB0_1422
